# one static s_setprio 1 for waves 4-7 through stage A and the work-item phase (lever 4), reset before the P3 GEMM
# baseline (speedup 1.0000x reference)
; __device__ __forceinline__ void chunkA_item(const Args& A, LAS unsigned char* lds, int tid, int lane, int wave, int ci, int ci_next, HeadConstA& H) {
;     ...
;     if (tid < 256) {
;         const int cp = tid >> 2, q = tid & 3;
;         f32x2_t xa[8], xb[8];
; #pragma unroll
;         for (int m = 0; m < 8; ++m) { xa[m] = (f32x2_t){0.f, 0.f}; xb[m] = (f32x2_t){0.f, 0.f}; }
;         const LAS float* Np = (const LAS float*)(lds + CA_N) + q * 16;
;         const LAS float* Ra = (const LAS float*)(lds + CA_RHS) + cp * 68; const LAS float* Rb = Ra + 64 * 68;
;         float a4[4], b4[4];
; #pragma unroll
;         for (int t = 0; t < 64; ++t) {
;             f32x2_t sa = {0.f, 0.f}, sb = {0.f, 0.f};
; #pragma unroll
;             for (int p = 0; p < ((t + 3) / 4 + 1) / 2; ++p) { const f32x2_t nv = *(const LAS f32x2_t*)(Np + t * 64 + 2 * p); sa += nv * xa[p]; sb += nv * xb[p]; }
;             float ua = sa.x + sa.y, ub = sb.x + sb.y;
;             ua += dppf<0xB1>(ua); ub += dppf<0xB1>(ub); ua += dppf<0x4E>(ua); ub += dppf<0x4E>(ub);
;             const float xta = Ra[t] - ua, xtb = Rb[t] - ub;
;             if (q == (t & 3)) { if ((t >> 2) & 1) { xa[t >> 3].y = xta; xb[t >> 3].y = xtb; } else { xa[t >> 3].x = xta; xb[t >> 3].x = xtb; } }
;             a4[t & 3] = xta; b4[t & 3] = xtb;
;             if ((t & 3) == 3 && q == 0) { *(LAS u32x2*)(lds + CA_XT + cp * 144 + (t - 3) * 2) = pack4(a4[0], a4[1], a4[2], a4[3]);
;                 *(LAS u32x2*)(lds + CA_XT + (64 + cp) * 144 + (t - 3) * 2) = pack4(b4[0], b4[1], b4[2], b4[3]); }
;         }
;     } else if (ci_next < 4096) {
;         const int cn = ci_next & 31, hn = (ci_next >> 5) & 7, bn = ci_next >> 8; const long rown = (long)bn * SEQ + cn * 64 - 1;
;         for (int l = tid - 256; l < 65 * 5; l += 256) { const int r = l / 5, sec = l % 5; long rr = rown + r; if (rr < 0) rr = 0;
;             const bf16_t* p = Z + rr * NZ + (sec == 0 ? hn * 64 : sec == 1 ? 512 + hn * 64 : sec == 2 ? 1024 + hn * 64 : sec == 3 ? 1536 : 1600);
;             unsigned dummy; asm volatile("global_load_dword %0, %1, off" : "=v"(dummy) : "v"(p) : "memory"); }
; __global__ void __launch_bounds__(512, 2) hymba_fwd(Args A) {
;     ...
;         { HeadConstA HC; HC.h = -1;
;           for (int it = blockIdx.x; it < N_CH; it += gridDim.x) chunkA_item(A, lds, tid, lane, wave, it, it + (int)gridDim.x, HC); }
.LBB0_147:
	v_readlane_b32 s98, v249, 3
	s_cmp_ge_u32 s98, 4
	s_cbranch_scc0 .Lprio_done
	s_setprio 1

; __global__ void __launch_bounds__(512, 2) hymba_fwd(Args A) {
;     ...
;         for (;;) {
;             if (tid == 0) *s_item = (int)atomicAdd(ctl + CW_WORK + 2, 1u);
;             __syncthreads();
;             const int r = *s_item;
;             __syncthreads();
;             if (r >= 256) break;
;             sscan_item(A, lds, tid, lane, wave, r >> 3, r & 7);
.LBB0_494:
	s_or_b64 exec, exec, s[4:5]
	s_setprio 0
	s_cmpk_lt_i32 s2, 0x200
	s_cselect_b64 s[4:5], -1, 0
	s_cmpk_gt_i32 s2, 0x1ff
	v_readfirstlane_b32 s16, v144
	s_barrier
	s_cbranch_scc1 .LBB0_500
	s_ashr_i32 s3, s2, 31
	s_lshr_b32 s3, s3, 29
	s_add_i32 s3, s2, s3
	s_and_b32 s6, s3, -8
	s_sub_i32 s8, s2, s6
	s_cmp_gt_i32 s8, -1
	s_cbranch_scc0 .LBB0_497
	s_lshl_b32 s9, s8, 6
	s_cbranch_execz .LBB0_498
	s_branch .LBB0_499
